# v18: v15 + lever 4 mirrored: one static s_setprio 1 for waves 0-3 over each GEMM phase, all per-segment flips deleted
# speedup vs baseline: 1.0008x; 1.0004x over previous
; __global__ void __launch_bounds__(NWAVES * 64, 2) mk_fwd(Args args) {
;     ...
;     if (IN(G_WIN)) {
;         {
;             pg8::Gemm g{(const bf16*)(ws + WS_X8), (const bf16*)(ws + WS_WIN8), M, NQKV, D / 2, D / 2, D / 2, 0}; pg8::StaticOrder S; S.init(M, NQKV, F.G, bx);
;             pg8::EpiWin8 E{(bf16*)(ws + WS_QKV), (bf16*)(ws + WS_Z), (bf16*)(ws + WS_GT), RSTD, (const float*)(ws + WS_SX), (const float*)(ws + WS_SW), 0};
;             pg8::gemm_phase<pg8::EpiWin8, pg8::StaticOrder, true, true, true>(F.lds + RING_OFF, g, S, E);
.LBB0_471:
	s_cmp_lt_i32 s4, 2
	s_cselect_b64 s[0:1], -1, 0
	s_cmp_gt_i32 s5, 1
	s_cselect_b64 s[2:3], -1, 0
	s_and_b64 s[0:1], s[0:1], s[2:3]
	s_andn2_b64 vcc, exec, s[0:1]
	s_cbranch_vccnz .LBB0_708
	v_readfirstlane_b32 s98, v0
	s_nop 3
	s_and_b32 s98, s98, 0x3ff
	s_lshr_b32 s98, s98, 6
	s_cmp_ge_u32 s98, 4
	s_cbranch_scc1 .Lprio_gwin
	s_setprio 1

; __global__ void __launch_bounds__(NWAVES * 64, 2) mk_fwd(Args args) {
;     ...
;     if (IN(G_LORA)) {
;         pg8::Gemm g{(const bf16*)(ws + WS_ALORA), (const bf16*)(ws + WS_WLORA), M, LORAN, LORAK, LORAK, LORAK, 1}; pg8::StaticOrder S; S.init(M, LORAN, F.G, bx);
;         pg8::EpiLora E{(bf16*)(ws + WS_EAG), F.in[9], F.in[11], (size_t)M * 2048};
;         pg8::gemm_phase<pg8::EpiLora, pg8::StaticOrder, true, true>(F.lds + RING_OFF, g, S, E);
.LBB0_1076:
	s_cmp_lt_i32 s4, 4
	s_cselect_b64 s[0:1], -1, 0
	s_cmp_gt_i32 s5, 3
	s_cselect_b64 s[2:3], -1, 0
	s_and_b64 s[0:1], s[0:1], s[2:3]
	s_andn2_b64 vcc, exec, s[0:1]
	s_cbranch_vccnz .LBB0_1193
	v_readfirstlane_b32 s98, v0
	s_nop 3
	s_and_b32 s98, s98, 0x3ff
	s_lshr_b32 s98, s98, 6
	s_cmp_ge_u32 s98, 4
	s_cbranch_scc1 .Lprio_lora
	s_setprio 1

; __global__ void __launch_bounds__(NWAVES * 64, 2) mk_fwd(Args args) {
;     ...
;     if (IN(G_ATTUP)) {
;         pg8::Gemm g{(const bf16*)(ws + WS_ATT), (const bf16*)(ws + WS_WATT), M, D, AOW, AOW, AOW, 0}; pg8::StaticOrder S; S.init(M, D, F.G, bx);
;         pg8::EpiB<2> E{(bf16*)(ws + WS_AD), D, nullptr, (const bf16*)(ws + WS_GT), nullptr, nullptr};
;         pg8::gemm_phase<pg8::EpiB<2>, pg8::StaticOrder, true, true>(F.lds + RING_OFF, g, S, E);
.LBB0_1520:
	s_cmp_lt_i32 s4, 8
	s_cselect_b64 s[0:1], -1, 0
	s_cmp_gt_i32 s5, 7
	s_cselect_b64 s[2:3], -1, 0
	s_and_b64 s[0:1], s[0:1], s[2:3]
	s_andn2_b64 vcc, exec, s[0:1]
	s_cbranch_vccnz .LBB0_1545
	v_readfirstlane_b32 s98, v0
	s_nop 3
	s_and_b32 s98, s98, 0x3ff
	s_lshr_b32 s98, s98, 6
	s_cmp_ge_u32 s98, 4
	s_cbranch_scc1 .Lprio_attup
	s_setprio 1

; #define GRID_BAR() xcd_barrier(bar)
; #define GRID_BAR() do {} while (0)
; __global__ void __launch_bounds__(NWAVES * 64, 2) mk_fwd(Args args) {
;     ...
;         rows_bf16_to_i8(F, (const bf16*)(ws + WS_MERGED), (const unsigned*)(ws + CTL_RMAX3), (unsigned*)(ws + WS_X8C), (float*)(ws + WS_SX3));
;         GRID_BAR();
;         pg8::Gemm g{(const bf16*)(ws + WS_X8C), (const bf16*)(ws + WS_W8O), M, D, D / 2, D / 2, D / 2, 0}; pg8::StaticOrder S; S.init(M, D, F.G, bx);
;         pg8::EpiF<0, true> E{F.in[0], F.out, nullptr, nullptr, XB, (float*)(ws + CTL_SS2), (unsigned*)(ws + CTL_RMAX2), (const float*)(ws + WS_SX3), (const float*)(ws + WS_SWO)};
;         pg8::gemm_phase<pg8::EpiF<0, true>, pg8::StaticOrder, true, true, true>(F.lds + RING_OFF, g, S, E);
.LBB0_1702:
	s_or_b64 exec, exec, s[0:1]
	v_readfirstlane_b32 s98, v0
	s_nop 3
	s_and_b32 s98, s98, 0x3ff
	s_lshr_b32 s98, s98, 6
	s_cmp_ge_u32 s98, 4
	s_cbranch_scc1 .Lprio_gout
	s_setprio 1

; __global__ void __launch_bounds__(NWAVES * 64, 2) mk_fwd(Args args) {
;     ...
;     if (IN(G_MLPIN)) {
;         pg8::Gemm g{(const bf16*)(ws + WS_X8B), (const bf16*)(ws + WS_W8M), M, DFF, D / 2, D / 2, D / 2, 0}; pg8::StaticOrder S; S.init(M, DFF, F.G, bx);
;         pg8::EpiMlp8 E{(bf16*)(ws + WS_HID), DFF, (const float*)(ws + CTL_SS2), (const float*)(ws + WS_SX2), (const float*)(ws + WS_SWM)};
;         pg8::gemm_phase<pg8::EpiMlp8, pg8::StaticOrder, true, true, true>(F.lds + RING_OFF, g, S, E);
.LBB0_1996:
	s_cmp_lt_i32 s72, 12
	s_cselect_b64 s[0:1], -1, 0
	s_cmp_gt_i32 s73, 11
	s_cselect_b64 s[2:3], -1, 0
	s_and_b64 s[0:1], s[0:1], s[2:3]
	s_andn2_b64 vcc, exec, s[0:1]
	v_readlane_b32 s70, v254, 6
	v_readlane_b32 s71, v254, 7
	s_cbranch_vccnz .LBB0_2075
	v_readfirstlane_b32 s98, v0
	s_nop 3
	s_and_b32 s98, s98, 0x3ff
	s_lshr_b32 s98, s98, 6
	s_cmp_ge_u32 s98, 4
	s_cbranch_scc1 .Lprio_mlpin
	s_setprio 1

; __global__ void __launch_bounds__(NWAVES * 64, 2) mk_fwd(Args args) {
;     ...
;     if (IN(G_MLPOUT)) {
;         pg8::Gemm g{(const bf16*)(ws + WS_HID), (const bf16*)(ws + WS_WMLPOUT), M, D, DFF, DFF, DFF, 0}; pg8::StaticOrder S; S.init(M, D, F.G, bx);
;         pg8::EpiF<0> E{F.out, F.out, nullptr, nullptr, XB, (float*)(ws + CTL_SS3), (unsigned*)(ws + CTL_RMAX4), nullptr, nullptr};
;         pg8::gemm_phase<pg8::EpiF<0>, pg8::StaticOrder, true, true>(F.lds + RING_OFF, g, S, E);
.LBB0_2075:
	s_cmp_lt_i32 s72, 13
	s_cselect_b64 s[0:1], -1, 0
	s_cmp_gt_i32 s73, 12
	s_cselect_b64 s[2:3], -1, 0
	s_and_b64 s[0:1], s[0:1], s[2:3]
	s_andn2_b64 vcc, exec, s[0:1]
	s_cbranch_vccnz .LBB0_2220
	v_readfirstlane_b32 s98, v0
	s_nop 3
	s_and_b32 s98, s98, 0x3ff
	s_lshr_b32 s98, s98, 6
	s_cmp_ge_u32 s98, 4
	s_cbranch_scc1 .Lprio_mlpout
	s_setprio 1

; __global__ void __launch_bounds__(NWAVES * 64, 2) mk_fwd(Args args) {
;     ...
;         pg8::Gemm g{(const bf16*)(ws + WS_PB), (const bf16*)(ws + WS_WPLEP), M, D, PLE, PLE, PLE, 0}; pg8::StaticOrder S; S.init(M, D, F.G, bx);
;         pg8::EpiB<0> E{(bf16*)(ws + WS_PP), D, nullptr, nullptr, nullptr, nullptr};
;         pg8::gemm_phase<pg8::EpiB<0>, pg8::StaticOrder, true, true>(F.lds + RING_OFF, g, S, E);
.LBB0_2228:
	v_readfirstlane_b32 s98, v0
	s_nop 3
	s_and_b32 s98, s98, 0x3ff
	s_lshr_b32 s98, s98, 6
	s_cmp_ge_u32 s98, 4
	s_cbranch_scc1 .Lprio_gpp
	s_setprio 1

; __global__ void __launch_bounds__(NWAVES * 64, 2) mk_fwd(Args args) {
;     ...
;     if (IN(G_PLE)) {
;         pg8::Gemm g{(const bf16*)(ws + WS_X8D), (const bf16*)(ws + WS_W8P), M, D, D / 2, D / 2, D / 2, 0}; pg8::StaticOrder S; S.init(M, D, F.G, bx);
;         pg8::EpiF<1, true> E{F.out, F.out, (const float*)(ws + CTL_SS3), (const bf16*)(ws + WS_PP), nullptr, nullptr, nullptr, (const float*)(ws + WS_SX4), (const float*)(ws + WS_SWP)};
;         pg8::gemm_phase<pg8::EpiF<1, true>, pg8::StaticOrder, true, true, true>(F.lds + RING_OFF, g, S, E);
.LBB0_2304:
	s_cmp_lt_i32 s72, 15
	s_cselect_b64 s[0:1], -1, 0
	s_cmp_gt_i32 s73, 14
	s_cselect_b64 s[2:3], -1, 0
	s_and_b64 s[0:1], s[0:1], s[2:3]
	s_andn2_b64 vcc, exec, s[0:1]
	s_cbranch_vccnz .LBB0_2329
	v_readfirstlane_b32 s98, v0
	s_nop 3
	s_and_b32 s98, s98, 0x3ff
	s_lshr_b32 s98, s98, 6
	s_cmp_ge_u32 s98, 4
	s_cbranch_scc1 .Lprio_ple
	s_setprio 1
